# RG-LRU scan loops (ctx+latent): base+immediate LDS addressing and a/u reads of the next 4 tokens in flight during the FMA chain
# speedup vs baseline: 1.0114x; 1.0085x over previous
.LBB0_469:
	v_add_u32_e32 v60, v193, v207
	ds_read_b128 v[48:51], v60 offset:16384
	ds_read_b128 v[52:55], v60 offset:18432
	ds_read_b128 v[56:59], v60 offset:20480
	ds_read_b128 v[60:63], v60 offset:22528
	v_add_u32_e32 v44, s26, v192
	v_lshl_add_u32 v179, v44, 7, 0
	v_add_u32_e32 v44, v179, v207
	s_waitcnt lgkmcnt(4)
	ds_read_b128 v[44:47], v44
	v_add_u32_e32 v68, v193, v208
	ds_read_b128 v[64:67], v68 offset:16384
	s_waitcnt lgkmcnt(1)
	v_mfma_f32_16x16x32_bf16 v[48:51], v[48:51], v[44:47], 0
	v_add3_u32 v162, v179, v212, v213
	v_mfma_f32_16x16x32_bf16 v[52:55], v[52:55], v[44:47], 0
	v_mfma_f32_16x16x32_bf16 v[56:59], v[56:59], v[44:47], 0
	v_mfma_f32_16x16x32_bf16 v[44:47], v[60:63], v[44:47], 0
	v_add_u32_e32 v60, v179, v208
	ds_read_b128 v[60:63], v60
	s_waitcnt lgkmcnt(0)
	v_mfma_f32_16x16x32_bf16 v[64:67], v[64:67], v[60:63], v[48:51]
	s_nop 2
	ds_read_b128 v[48:51], v68 offset:18432
	s_waitcnt lgkmcnt(0)
	v_mfma_f32_16x16x32_bf16 v[48:51], v[48:51], v[60:63], v[52:55]
	s_nop 2
	ds_read_b128 v[52:55], v68 offset:20480
	s_waitcnt lgkmcnt(0)
	v_mfma_f32_16x16x32_bf16 v[52:55], v[52:55], v[60:63], v[56:59]
	s_nop 2
	ds_read_b128 v[56:59], v68 offset:22528
	s_waitcnt lgkmcnt(0)
	s_barrier
	v_mfma_f32_16x16x32_bf16 v[44:47], v[56:59], v[60:63], v[44:47]
	ds_read_b128 v[68:71], v209
	ds_read_b128 v[60:63], v210
	ds_read_b128 v[56:59], v211
	ds_read_b64 v[164:165], v162
	s_waitcnt lgkmcnt(3)
	v_add_f32_e32 v64, v64, v68
	v_mul_f32_e32 v64, 0xbfb8aa3b, v64
	v_exp_f32_e32 v64, v64
	s_waitcnt lgkmcnt(2)
	v_add_f32_e32 v52, v52, v60
	v_mul_f32_e32 v52, 0xbfb8aa3b, v52
	v_exp_f32_e32 v60, v52
	v_add_f32_e32 v64, 1.0, v64
	v_div_scale_f32 v68, s[0:1], v64, v64, 1.0
	v_rcp_f32_e32 v180, v68
	v_add_f32_e32 v53, v53, v61
	v_mul_f32_e32 v53, 0xbfb8aa3b, v53
	v_exp_f32_e32 v61, v53
	v_fma_f32 v181, -v68, v180, 1.0
	v_fmac_f32_e32 v180, v181, v180
	v_div_scale_f32 v181, vcc, 1.0, v64, 1.0
	v_mul_f32_e32 v182, v181, v180
	v_fma_f32 v186, -v68, v182, v181
	v_fmac_f32_e32 v182, v186, v180
	v_fma_f32 v68, -v68, v182, v181
	v_div_fmas_f32 v68, v68, v180, v182
	v_div_fixup_f32 v64, v68, v64, 1.0
	v_mul_f32_e32 v52, 0xc1000000, v64
	s_waitcnt lgkmcnt(1)
	v_mul_f32_e32 v52, v56, v52
	v_mul_f32_e32 v52, 0x3fb8aa3b, v52
	v_exp_f32_e32 v52, v52
	v_add_f32_e32 v54, v54, v62
	v_mul_f32_e32 v54, 0xbfb8aa3b, v54
	v_exp_f32_e32 v62, v54
	v_fma_f32 v56, -v52, v52, 1.0
	v_max_f32_e32 v56, 0, v56
	v_cmp_gt_f32_e32 vcc, s10, v56
	v_mul_f32_e32 v64, 0x4f800000, v56
	v_add_f32_e32 v55, v55, v63
	v_cndmask_b32_e32 v56, v56, v64, vcc
	v_sqrt_f32_e32 v64, v56
	v_mul_f32_e32 v55, 0xbfb8aa3b, v55
	v_exp_f32_e32 v63, v55
	v_pk_add_f32 v[60:61], v[60:61], 1.0 op_sel_hi:[1,0]
	v_add_u32_e32 v68, -1, v64
	v_fma_f32 v180, -v68, v64, v56
	v_cmp_ge_f32_e64 s[0:1], 0, v180
	v_add_u32_e32 v180, 1, v64
	v_pk_add_f32 v[62:63], v[62:63], 1.0 op_sel_hi:[1,0]
	v_cndmask_b32_e64 v68, v64, v68, s[0:1]
	v_fma_f32 v64, -v180, v64, v56
	v_cmp_lt_f32_e64 s[0:1], 0, v64
	s_waitcnt lgkmcnt(0)
	v_lshlrev_b32_e32 v162, 16, v164
	v_and_b32_e32 v163, 0xffff0000, v164
	v_cndmask_b32_e64 v64, v68, v180, s[0:1]
	v_mul_f32_e32 v68, 0x37800000, v64
	v_cndmask_b32_e32 v64, v64, v68, vcc
	v_cmp_class_f32_e32 vcc, v56, v169
	v_lshlrev_b32_e32 v164, 16, v165
	v_and_b32_e32 v165, 0xffff0000, v165
	v_cndmask_b32_e32 v56, v64, v56, vcc
	v_add_f32_e32 v64, v65, v69
	v_mul_f32_e32 v64, 0xbfb8aa3b, v64
	v_exp_f32_e32 v64, v64
	s_nop 0
	v_add_f32_e32 v64, 1.0, v64
	v_div_scale_f32 v65, s[0:1], v64, v64, 1.0
	v_rcp_f32_e32 v68, v65
	s_nop 0
	v_fma_f32 v69, -v65, v68, 1.0
	v_fmac_f32_e32 v68, v69, v68
	v_div_scale_f32 v69, vcc, 1.0, v64, 1.0
	v_mul_f32_e32 v180, v69, v68
	v_fma_f32 v181, -v65, v180, v69
	v_fmac_f32_e32 v180, v181, v68
	v_fma_f32 v65, -v65, v180, v69
	v_div_fmas_f32 v65, v65, v68, v180
	v_div_fixup_f32 v64, v65, v64, 1.0
	v_mul_f32_e32 v53, 0xc1000000, v64
	v_mul_f32_e32 v53, v57, v53
	v_mul_f32_e32 v53, 0x3fb8aa3b, v53
	v_exp_f32_e32 v53, v53
	s_nop 0
	v_fma_f32 v57, -v53, v53, 1.0
	v_max_f32_e32 v57, 0, v57
	v_cmp_gt_f32_e32 vcc, s10, v57
	v_mul_f32_e32 v64, 0x4f800000, v57
	s_nop 0
	v_cndmask_b32_e32 v57, v57, v64, vcc
	v_sqrt_f32_e32 v64, v57
	s_nop 0
	v_add_u32_e32 v65, -1, v64
	v_fma_f32 v68, -v65, v64, v57
	v_cmp_ge_f32_e64 s[0:1], 0, v68
	v_add_u32_e32 v68, 1, v64
	s_nop 0
	v_cndmask_b32_e64 v65, v64, v65, s[0:1]
	v_fma_f32 v64, -v68, v64, v57
	v_cmp_lt_f32_e64 s[0:1], 0, v64
	s_nop 1
	v_cndmask_b32_e64 v64, v65, v68, s[0:1]
	v_mul_f32_e32 v65, 0x37800000, v64
	v_cndmask_b32_e32 v64, v64, v65, vcc
	v_cmp_class_f32_e32 vcc, v57, v169
	s_nop 1
	v_cndmask_b32_e32 v57, v64, v57, vcc
	v_add_f32_e32 v64, v66, v70
	v_mul_f32_e32 v64, 0xbfb8aa3b, v64
	v_exp_f32_e32 v64, v64
	s_nop 0
	v_add_f32_e32 v64, 1.0, v64
	v_div_scale_f32 v65, s[0:1], v64, v64, 1.0
	v_rcp_f32_e32 v66, v65
	s_nop 0
	v_fma_f32 v68, -v65, v66, 1.0
	v_fmac_f32_e32 v66, v68, v66
	v_div_scale_f32 v68, vcc, 1.0, v64, 1.0
	v_mul_f32_e32 v69, v68, v66
	v_fma_f32 v70, -v65, v69, v68
	v_fmac_f32_e32 v69, v70, v66
	v_fma_f32 v65, -v65, v69, v68
	v_div_fmas_f32 v65, v65, v66, v69
	v_div_fixup_f32 v64, v65, v64, 1.0
	v_mul_f32_e32 v54, 0xc1000000, v64
	v_mul_f32_e32 v54, v58, v54
	v_mul_f32_e32 v54, 0x3fb8aa3b, v54
	v_exp_f32_e32 v54, v54
	s_nop 0
	v_fma_f32 v58, -v54, v54, 1.0
	v_max_f32_e32 v58, 0, v58
	v_cmp_gt_f32_e32 vcc, s10, v58
	v_mul_f32_e32 v64, 0x4f800000, v58
	s_nop 0
	v_cndmask_b32_e32 v58, v58, v64, vcc
	v_sqrt_f32_e32 v64, v58
	s_nop 0
	v_add_u32_e32 v65, -1, v64
	v_fma_f32 v66, -v65, v64, v58
	v_cmp_ge_f32_e64 s[0:1], 0, v66
	v_add_u32_e32 v66, 1, v64
	s_nop 0
	v_cndmask_b32_e64 v65, v64, v65, s[0:1]
	v_fma_f32 v64, -v66, v64, v58
	v_cmp_lt_f32_e64 s[0:1], 0, v64
	s_nop 1
	v_cndmask_b32_e64 v64, v65, v66, s[0:1]
	v_mul_f32_e32 v65, 0x37800000, v64
	v_cndmask_b32_e32 v64, v64, v65, vcc
	v_cmp_class_f32_e32 vcc, v58, v169
	s_nop 1
	v_cndmask_b32_e32 v58, v64, v58, vcc
	v_add_f32_e32 v64, v67, v71
	v_mul_f32_e32 v64, 0xbfb8aa3b, v64
	v_exp_f32_e32 v64, v64
	s_nop 0
	v_add_f32_e32 v64, 1.0, v64
	v_div_scale_f32 v65, s[0:1], v64, v64, 1.0
	v_rcp_f32_e32 v66, v65
	s_nop 0
	v_fma_f32 v67, -v65, v66, 1.0
	v_fmac_f32_e32 v66, v67, v66
	v_div_scale_f32 v67, vcc, 1.0, v64, 1.0
	v_mul_f32_e32 v68, v67, v66
	v_fma_f32 v69, -v65, v68, v67
	v_fmac_f32_e32 v68, v69, v66
	v_fma_f32 v65, -v65, v68, v67
	v_div_fmas_f32 v65, v65, v66, v68
	v_div_fixup_f32 v64, v65, v64, 1.0
	v_mul_f32_e32 v55, 0xc1000000, v64
	v_mul_f32_e32 v55, v59, v55
	v_mul_f32_e32 v55, 0x3fb8aa3b, v55
	v_exp_f32_e32 v55, v55
	s_nop 0
	v_fma_f32 v59, -v55, v55, 1.0
	v_max_f32_e32 v59, 0, v59
	v_cmp_gt_f32_e32 vcc, s10, v59
	v_mul_f32_e32 v64, 0x4f800000, v59
	s_nop 0
	v_cndmask_b32_e32 v59, v59, v64, vcc
	v_sqrt_f32_e32 v64, v59
	s_nop 0
	v_add_u32_e32 v65, -1, v64
	v_fma_f32 v66, -v65, v64, v59
	v_cmp_ge_f32_e64 s[0:1], 0, v66
	v_add_u32_e32 v66, 1, v64
	s_nop 0
	v_cndmask_b32_e64 v65, v64, v65, s[0:1]
	v_fma_f32 v64, -v66, v64, v59
	v_cmp_lt_f32_e64 s[0:1], 0, v64
	s_nop 1
	v_cndmask_b32_e64 v64, v65, v66, s[0:1]
	v_mul_f32_e32 v65, 0x37800000, v64
	v_cndmask_b32_e32 v64, v64, v65, vcc
	v_cmp_class_f32_e32 vcc, v59, v169
	s_nop 1
	v_cndmask_b32_e32 v59, v64, v59, vcc
	v_div_scale_f32 v64, s[0:1], v63, v63, 1.0
	v_rcp_f32_e32 v65, v64
	s_nop 0
	v_fma_f32 v66, -v64, v65, 1.0
	v_fmac_f32_e32 v65, v66, v65
	v_div_scale_f32 v66, vcc, 1.0, v63, 1.0
	v_mul_f32_e32 v67, v66, v65
	v_fma_f32 v68, -v64, v67, v66
	v_fmac_f32_e32 v67, v68, v65
	v_fma_f32 v64, -v64, v67, v66
	v_div_fmas_f32 v64, v64, v65, v67
	v_div_fixup_f32 v63, v64, v63, 1.0
	v_div_scale_f32 v64, s[0:1], v62, v62, 1.0
	v_rcp_f32_e32 v65, v64
	s_nop 0
	v_fma_f32 v66, -v64, v65, 1.0
	v_fmac_f32_e32 v65, v66, v65
	v_div_scale_f32 v66, vcc, 1.0, v62, 1.0
	v_mul_f32_e32 v67, v66, v65
	v_fma_f32 v68, -v64, v67, v66
	v_fmac_f32_e32 v67, v68, v65
	v_fma_f32 v64, -v64, v67, v66
	v_div_fmas_f32 v64, v64, v65, v67
	v_div_fixup_f32 v62, v64, v62, 1.0
	v_div_scale_f32 v64, s[0:1], v61, v61, 1.0
	v_rcp_f32_e32 v65, v64
	v_pk_mul_f32 v[58:59], v[62:63], v[58:59]
	v_fma_f32 v66, -v64, v65, 1.0
	v_fmac_f32_e32 v65, v66, v65
	v_div_scale_f32 v66, vcc, 1.0, v61, 1.0
	v_mul_f32_e32 v67, v66, v65
	v_fma_f32 v68, -v64, v67, v66
	v_fmac_f32_e32 v67, v68, v65
	v_fma_f32 v64, -v64, v67, v66
	v_div_fmas_f32 v64, v64, v65, v67
	v_div_fixup_f32 v61, v64, v61, 1.0
	v_div_scale_f32 v64, s[0:1], v60, v60, 1.0
	v_rcp_f32_e32 v65, v64
	v_pk_mul_f32 v[58:59], v[58:59], v[164:165]
	v_fma_f32 v66, -v64, v65, 1.0
	v_fmac_f32_e32 v65, v66, v65
	v_div_scale_f32 v66, vcc, 1.0, v60, 1.0
	v_mul_f32_e32 v67, v66, v65
	v_fma_f32 v68, -v64, v67, v66
	v_fmac_f32_e32 v67, v68, v65
	v_fma_f32 v64, -v64, v67, v66
	v_div_fmas_f32 v64, v64, v65, v67
	v_div_fixup_f32 v60, v64, v60, 1.0
	v_pk_mul_f32 v[56:57], v[60:61], v[56:57]
	v_add3_u32 v64, v179, v218, v213
	v_pk_mul_f32 v[56:57], v[56:57], v[162:163]
	ds_write_b128 v214, v[52:55] offset:32768
	ds_write_b128 v214, v[56:59] offset:50176
	ds_read_b128 v[60:63], v215
	ds_read_b128 v[56:59], v216
	ds_read_b128 v[52:55], v217
	ds_read_b64 v[66:67], v64
	s_waitcnt lgkmcnt(3)
	v_add_f32_e32 v48, v48, v60
	v_mul_f32_e32 v48, 0xbfb8aa3b, v48
	v_exp_f32_e32 v48, v48
	s_waitcnt lgkmcnt(2)
	v_add_f32_e32 v44, v44, v56
	v_mul_f32_e32 v44, 0xbfb8aa3b, v44
	v_exp_f32_e32 v56, v44
	v_add_f32_e32 v48, 1.0, v48
	v_div_scale_f32 v60, s[0:1], v48, v48, 1.0
	v_rcp_f32_e32 v68, v60
	v_add_f32_e32 v49, v49, v61
	v_mul_f32_e32 v49, 0xbfb8aa3b, v49
	v_exp_f32_e32 v49, v49
	v_fma_f32 v69, -v60, v68, 1.0
	v_fmac_f32_e32 v68, v69, v68
	v_div_scale_f32 v69, vcc, 1.0, v48, 1.0
	v_mul_f32_e32 v70, v69, v68
	v_fma_f32 v71, -v60, v70, v69
	v_fmac_f32_e32 v70, v71, v68
	v_fma_f32 v60, -v60, v70, v69
	v_div_fmas_f32 v60, v60, v68, v70
	v_div_fixup_f32 v48, v60, v48, 1.0
	v_mul_f32_e32 v44, 0xc1000000, v48
	s_waitcnt lgkmcnt(1)
	v_mul_f32_e32 v44, v52, v44
	v_mul_f32_e32 v44, 0x3fb8aa3b, v44
	v_exp_f32_e32 v44, v44
	v_add_f32_e32 v49, 1.0, v49
	v_add_f32_e32 v45, v45, v57
	v_mul_f32_e32 v45, 0xbfb8aa3b, v45
	v_fma_f32 v48, -v44, v44, 1.0
	v_max_f32_e32 v48, 0, v48
	v_cmp_gt_f32_e32 vcc, s10, v48
	v_mul_f32_e32 v52, 0x4f800000, v48
	v_exp_f32_e32 v57, v45
	v_cndmask_b32_e32 v48, v48, v52, vcc
	v_sqrt_f32_e32 v52, v48
	v_add_f32_e32 v50, v50, v62
	v_mul_f32_e32 v50, 0xbfb8aa3b, v50
	v_exp_f32_e32 v50, v50
	v_add_u32_e32 v60, -1, v52
	v_fma_f32 v68, -v60, v52, v48
	v_cmp_ge_f32_e64 s[0:1], 0, v68
	v_add_u32_e32 v68, 1, v52
	v_add_f32_e32 v50, 1.0, v50
	v_cndmask_b32_e64 v60, v52, v60, s[0:1]
	v_fma_f32 v52, -v68, v52, v48
	v_cmp_lt_f32_e64 s[0:1], 0, v52
	v_add_f32_e32 v46, v46, v58
	v_mul_f32_e32 v46, 0xbfb8aa3b, v46
	v_cndmask_b32_e64 v52, v60, v68, s[0:1]
	v_mul_f32_e32 v60, 0x37800000, v52
	v_cndmask_b32_e32 v52, v52, v60, vcc
	v_cmp_class_f32_e32 vcc, v48, v169
	v_add_f32_e32 v51, v51, v63
	v_mul_f32_e32 v51, 0xbfb8aa3b, v51
	v_cndmask_b32_e32 v48, v52, v48, vcc
	v_div_scale_f32 v52, s[0:1], v49, v49, 1.0
	v_rcp_f32_e32 v60, v52
	v_exp_f32_e32 v51, v51
	v_add_f32_e32 v47, v47, v59
	v_mul_f32_e32 v47, 0xbfb8aa3b, v47
	v_fma_f32 v61, -v52, v60, 1.0
	v_fmac_f32_e32 v60, v61, v60
	v_div_scale_f32 v61, vcc, 1.0, v49, 1.0
	v_mul_f32_e32 v68, v61, v60
	v_fma_f32 v69, -v52, v68, v61
	v_fmac_f32_e32 v68, v69, v60
	v_fma_f32 v52, -v52, v68, v61
	v_div_fmas_f32 v52, v52, v60, v68
	v_div_fixup_f32 v49, v52, v49, 1.0
	v_mul_f32_e32 v45, 0xc1000000, v49
	v_mul_f32_e32 v45, v53, v45
	v_mul_f32_e32 v45, 0x3fb8aa3b, v45
	v_exp_f32_e32 v45, v45
	v_add_f32_e32 v51, 1.0, v51
	s_waitcnt lgkmcnt(0)
	v_lshlrev_b32_e32 v64, 16, v66
	v_and_b32_e32 v65, 0xffff0000, v66
	v_fma_f32 v49, -v45, v45, 1.0
	v_max_f32_e32 v49, 0, v49
	v_cmp_gt_f32_e32 vcc, s10, v49
	v_mul_f32_e32 v52, 0x4f800000, v49
	v_lshlrev_b32_e32 v66, 16, v67
	v_cndmask_b32_e32 v49, v49, v52, vcc
	v_sqrt_f32_e32 v52, v49
	v_and_b32_e32 v67, 0xffff0000, v67
	v_add_u32_e32 v53, -1, v52
	v_fma_f32 v60, -v53, v52, v49
	v_cmp_ge_f32_e64 s[0:1], 0, v60
	v_add_u32_e32 v60, 1, v52
	s_nop 0
	v_cndmask_b32_e64 v53, v52, v53, s[0:1]
	v_fma_f32 v52, -v60, v52, v49
	v_cmp_lt_f32_e64 s[0:1], 0, v52
	s_nop 1
	v_cndmask_b32_e64 v52, v53, v60, s[0:1]
	v_mul_f32_e32 v53, 0x37800000, v52
	v_cndmask_b32_e32 v52, v52, v53, vcc
	v_cmp_class_f32_e32 vcc, v49, v169
	s_nop 1
	v_cndmask_b32_e32 v49, v52, v49, vcc
	v_div_scale_f32 v52, s[0:1], v50, v50, 1.0
	v_rcp_f32_e32 v53, v52
	s_nop 0
	v_fma_f32 v60, -v52, v53, 1.0
	v_fmac_f32_e32 v53, v60, v53
	v_div_scale_f32 v60, vcc, 1.0, v50, 1.0
	v_mul_f32_e32 v61, v60, v53
	v_fma_f32 v62, -v52, v61, v60
	v_fmac_f32_e32 v61, v62, v53
	v_fma_f32 v52, -v52, v61, v60
	v_div_fmas_f32 v52, v52, v53, v61
	v_div_fixup_f32 v50, v52, v50, 1.0
	v_exp_f32_e32 v52, v46
	v_mul_f32_e32 v46, 0xc1000000, v50
	v_mul_f32_e32 v46, v54, v46
	v_mul_f32_e32 v46, 0x3fb8aa3b, v46
	v_exp_f32_e32 v46, v46
	s_nop 0
	v_fma_f32 v50, -v46, v46, 1.0
	v_max_f32_e32 v50, 0, v50
	v_cmp_gt_f32_e32 vcc, s10, v50
	v_mul_f32_e32 v53, 0x4f800000, v50
	s_nop 0
	v_cndmask_b32_e32 v50, v50, v53, vcc
	v_sqrt_f32_e32 v53, v50
	s_nop 0
	v_add_u32_e32 v54, -1, v53
	v_fma_f32 v58, -v54, v53, v50
	v_cmp_ge_f32_e64 s[0:1], 0, v58
	v_add_u32_e32 v58, 1, v53
	s_nop 0
	v_cndmask_b32_e64 v54, v53, v54, s[0:1]
	v_fma_f32 v53, -v58, v53, v50
	v_cmp_lt_f32_e64 s[0:1], 0, v53
	s_nop 1
	v_cndmask_b32_e64 v53, v54, v58, s[0:1]
	v_mul_f32_e32 v54, 0x37800000, v53
	v_cndmask_b32_e32 v53, v53, v54, vcc
	v_cmp_class_f32_e32 vcc, v50, v169
	s_nop 1
	v_cndmask_b32_e32 v50, v53, v50, vcc
	v_div_scale_f32 v53, s[0:1], v51, v51, 1.0
	v_rcp_f32_e32 v54, v53
	s_nop 0
	v_fma_f32 v58, -v53, v54, 1.0
	v_fmac_f32_e32 v54, v58, v54
	v_div_scale_f32 v58, vcc, 1.0, v51, 1.0
	v_mul_f32_e32 v60, v58, v54
	v_fma_f32 v61, -v53, v60, v58
	v_fmac_f32_e32 v60, v61, v54
	v_fma_f32 v53, -v53, v60, v58
	v_div_fmas_f32 v53, v53, v54, v60
	v_div_fixup_f32 v51, v53, v51, 1.0
	v_exp_f32_e32 v53, v47
	v_mul_f32_e32 v47, 0xc1000000, v51
	v_mul_f32_e32 v47, v55, v47
	v_mul_f32_e32 v47, 0x3fb8aa3b, v47
	v_exp_f32_e32 v47, v47
	v_pk_add_f32 v[52:53], v[52:53], 1.0 op_sel_hi:[1,0]
	v_fma_f32 v51, -v47, v47, 1.0
	v_max_f32_e32 v51, 0, v51
	v_cmp_gt_f32_e32 vcc, s10, v51
	v_mul_f32_e32 v54, 0x4f800000, v51
	s_nop 0
	v_cndmask_b32_e32 v51, v51, v54, vcc
	v_sqrt_f32_e32 v54, v51
	s_nop 0
	v_add_u32_e32 v55, -1, v54
	v_fma_f32 v58, -v55, v54, v51
	v_cmp_ge_f32_e64 s[0:1], 0, v58
	v_add_u32_e32 v58, 1, v54
	s_nop 0
	v_cndmask_b32_e64 v55, v54, v55, s[0:1]
	v_fma_f32 v54, -v58, v54, v51
	v_cmp_lt_f32_e64 s[0:1], 0, v54
	s_nop 1
	v_cndmask_b32_e64 v54, v55, v58, s[0:1]
	v_mul_f32_e32 v55, 0x37800000, v54
	v_cndmask_b32_e32 v54, v54, v55, vcc
	v_cmp_class_f32_e32 vcc, v51, v169
	s_nop 1
	v_cndmask_b32_e32 v51, v54, v51, vcc
	v_pk_add_f32 v[54:55], v[56:57], 1.0 op_sel_hi:[1,0]
	v_div_scale_f32 v56, s[0:1], v53, v53, 1.0
	v_rcp_f32_e32 v57, v56
	s_nop 0
	v_fma_f32 v58, -v56, v57, 1.0
	v_fmac_f32_e32 v57, v58, v57
	v_div_scale_f32 v58, vcc, 1.0, v53, 1.0
	v_mul_f32_e32 v59, v58, v57
	v_fma_f32 v60, -v56, v59, v58
	v_fmac_f32_e32 v59, v60, v57
	v_fma_f32 v56, -v56, v59, v58
	v_div_fmas_f32 v56, v56, v57, v59
	v_div_fixup_f32 v53, v56, v53, 1.0
	v_div_scale_f32 v56, s[0:1], v52, v52, 1.0
	v_rcp_f32_e32 v57, v56
	s_nop 0
	v_fma_f32 v58, -v56, v57, 1.0
	v_fmac_f32_e32 v57, v58, v57
	v_div_scale_f32 v58, vcc, 1.0, v52, 1.0
	v_mul_f32_e32 v59, v58, v57
	v_fma_f32 v60, -v56, v59, v58
	v_fmac_f32_e32 v59, v60, v57
	v_fma_f32 v56, -v56, v59, v58
	v_div_fmas_f32 v56, v56, v57, v59
	v_div_fixup_f32 v52, v56, v52, 1.0
	v_div_scale_f32 v56, s[0:1], v55, v55, 1.0
	v_rcp_f32_e32 v57, v56
	v_pk_mul_f32 v[50:51], v[52:53], v[50:51]
	v_fma_f32 v58, -v56, v57, 1.0
	v_fmac_f32_e32 v57, v58, v57
	v_div_scale_f32 v58, vcc, 1.0, v55, 1.0
	v_mul_f32_e32 v59, v58, v57
	v_fma_f32 v60, -v56, v59, v58
	v_fmac_f32_e32 v59, v60, v57
	v_fma_f32 v56, -v56, v59, v58
	v_div_fmas_f32 v56, v56, v57, v59
	v_div_fixup_f32 v55, v56, v55, 1.0
	v_div_scale_f32 v56, s[0:1], v54, v54, 1.0
	v_rcp_f32_e32 v57, v56
	v_pk_mul_f32 v[50:51], v[50:51], v[66:67]
	v_fma_f32 v58, -v56, v57, 1.0
	v_fmac_f32_e32 v57, v58, v57
	v_div_scale_f32 v58, vcc, 1.0, v54, 1.0
	v_mul_f32_e32 v59, v58, v57
	v_fma_f32 v60, -v56, v59, v58
	v_fmac_f32_e32 v59, v60, v57
	v_fma_f32 v56, -v56, v59, v58
	v_div_fmas_f32 v56, v56, v57, v59
	v_div_fixup_f32 v54, v56, v54, 1.0
	v_pk_mul_f32 v[48:49], v[54:55], v[48:49]
	s_nop 0
	v_pk_mul_f32 v[48:49], v[48:49], v[64:65]
	ds_write_b128 v214, v[44:47] offset:32832
	ds_write_b128 v214, v[48:51] offset:50240
	s_waitcnt lgkmcnt(0)
	s_barrier
	s_and_saveexec_b64 s[0:1], s[38:39]
	s_cbranch_execz .LBB0_472
	s_mov_b32 s28, 0
	s_and_b64 vcc, s[88:89], exec
	s_cbranch_scc0 .Lscan32_rinit
	v_mov_b32_e32 v60, v195
	ds_read_b32 v44, v60 offset:32768
	ds_read_b32 v45, v60 offset:50176
	ds_read_b32 v46, v60 offset:32912
	ds_read_b32 v47, v60 offset:50320
	ds_read_b32 v48, v60 offset:33056
	ds_read_b32 v49, v60 offset:50464
	ds_read_b32 v50, v60 offset:33200
	ds_read_b32 v51, v60 offset:50608
	ds_read_b32 v52, v60 offset:32768
	ds_read_b32 v53, v60 offset:32768
	ds_read_b32 v54, v60 offset:32768
	ds_read_b32 v55, v60 offset:32768
.Lscan32_fwd:
	s_waitcnt lgkmcnt(10)
	v_fmac_f32_e32 v45, v168, v44
	ds_read_b32 v52, v60 offset:33344
	ds_read_b32 v53, v60 offset:50752
	s_waitcnt lgkmcnt(10)
	v_fmac_f32_e32 v47, v45, v46
	ds_read_b32 v54, v60 offset:33488
	ds_read_b32 v55, v60 offset:50896
	s_waitcnt lgkmcnt(10)
	v_fmac_f32_e32 v49, v47, v48
	ds_read_b32 v56, v60 offset:33632
	ds_read_b32 v57, v60 offset:51040
	s_waitcnt lgkmcnt(10)
	v_fmac_f32_e32 v51, v49, v50
	ds_read_b32 v58, v60 offset:33776
	ds_read_b32 v59, v60 offset:51184
	s_waitcnt lgkmcnt(8)
	ds_write_b32 v60, v45 offset:50176
	ds_write_b32 v60, v47 offset:50320
	ds_write_b32 v60, v49 offset:50464
	ds_write_b32 v60, v51 offset:50608
	v_add_u32_e32 v61, 0x480, v60
	s_waitcnt lgkmcnt(10)
	v_fmac_f32_e32 v53, v51, v52
	ds_read_b32 v44, v61 offset:32768
	ds_read_b32 v45, v61 offset:50176
	s_waitcnt lgkmcnt(10)
	v_fmac_f32_e32 v55, v53, v54
	ds_read_b32 v46, v61 offset:32912
	ds_read_b32 v47, v61 offset:50320
	s_waitcnt lgkmcnt(10)
	v_fmac_f32_e32 v57, v55, v56
	ds_read_b32 v48, v61 offset:33056
	ds_read_b32 v49, v61 offset:50464
	s_waitcnt lgkmcnt(10)
	v_mov_b32_e32 v168, v59
	v_fmac_f32_e32 v168, v57, v58
	ds_read_b32 v50, v61 offset:33200
	ds_read_b32 v51, v61 offset:50608
	s_waitcnt lgkmcnt(8)
	ds_write_b32 v60, v53 offset:50752
	ds_write_b32 v60, v55 offset:50896
	ds_write_b32 v60, v57 offset:51040
	ds_write_b32 v60, v168 offset:51184
	v_mov_b32_e32 v60, v61
	s_add_i32 s28, s28, 8
	s_cmp_lt_u32 s28, 64
	s_cbranch_scc1 .Lscan32_fwd
	s_branch .Lscan32_done
.Lscan32_rinit:
	v_add_u32_e32 v60, 8064, v195
	ds_read_b32 v44, v60 offset:33776
	ds_read_b32 v45, v60 offset:51184
	ds_read_b32 v46, v60 offset:33632
	ds_read_b32 v47, v60 offset:51040
	ds_read_b32 v48, v60 offset:33488
	ds_read_b32 v49, v60 offset:50896
	ds_read_b32 v50, v60 offset:33344
	ds_read_b32 v51, v60 offset:50752
	ds_read_b32 v52, v60 offset:32768
	ds_read_b32 v53, v60 offset:32768
	ds_read_b32 v54, v60 offset:32768
	ds_read_b32 v55, v60 offset:32768
.Lscan32_rev:
	s_waitcnt lgkmcnt(10)
	v_fmac_f32_e32 v45, v168, v44
	ds_read_b32 v52, v60 offset:33200
	ds_read_b32 v53, v60 offset:50608
	s_waitcnt lgkmcnt(10)
	v_fmac_f32_e32 v47, v45, v46
	ds_read_b32 v54, v60 offset:33056
	ds_read_b32 v55, v60 offset:50464
	s_waitcnt lgkmcnt(10)
	v_fmac_f32_e32 v49, v47, v48
	ds_read_b32 v56, v60 offset:32912
	ds_read_b32 v57, v60 offset:50320
	s_waitcnt lgkmcnt(10)
	v_fmac_f32_e32 v51, v49, v50
	ds_read_b32 v58, v60 offset:32768
	ds_read_b32 v59, v60 offset:50176
	s_waitcnt lgkmcnt(8)
	ds_write_b32 v60, v45 offset:51184
	ds_write_b32 v60, v47 offset:51040
	ds_write_b32 v60, v49 offset:50896
	ds_write_b32 v60, v51 offset:50752
	v_add_u32_e32 v61, 0xfffffb80, v60
	s_waitcnt lgkmcnt(10)
	v_fmac_f32_e32 v53, v51, v52
	ds_read_b32 v44, v61 offset:33776
	ds_read_b32 v45, v61 offset:51184
	s_waitcnt lgkmcnt(10)
	v_fmac_f32_e32 v55, v53, v54
	ds_read_b32 v46, v61 offset:33632
	ds_read_b32 v47, v61 offset:51040
	s_waitcnt lgkmcnt(10)
	v_fmac_f32_e32 v57, v55, v56
	ds_read_b32 v48, v61 offset:33488
	ds_read_b32 v49, v61 offset:50896
	s_waitcnt lgkmcnt(10)
	v_mov_b32_e32 v168, v59
	v_fmac_f32_e32 v168, v57, v58
	ds_read_b32 v50, v61 offset:33344
	ds_read_b32 v51, v61 offset:50752
	s_waitcnt lgkmcnt(8)
	ds_write_b32 v60, v53 offset:50608
	ds_write_b32 v60, v55 offset:50464
	ds_write_b32 v60, v57 offset:50320
	ds_write_b32 v60, v168 offset:50176
	v_mov_b32_e32 v60, v61
	s_add_i32 s28, s28, 8
	s_cmp_lt_u32 s28, 64
	s_cbranch_scc1 .Lscan32_rev
.Lscan32_done:
.LBB0_472:
	s_or_b64 exec, exec, s[0:1]
	s_waitcnt lgkmcnt(0)
	s_barrier
	ds_read_b32 v47, v219 offset:50176
	v_add_u32_e32 v46, s26, v175
	v_add_u32_e32 v44, v46, v199
	v_ashrrev_i32_e32 v45, 31, v44
	s_xor_b64 s[28:29], s[40:41], -1
	s_mov_b64 s[0:1], -1
	s_and_b64 vcc, exec, s[2:3]
	v_lshlrev_b64 v[44:45], 11, v[44:45]
	s_cbranch_vccz .LBB0_474
	s_waitcnt vmcnt(14)
	v_mul_f32_e32 v48, 0x3d372713, v235
	v_mul_f32_e32 v48, v235, v48
	v_fma_f32 v48, v235, v48, v235
	v_mul_f32_e32 v48, 0x3f4c422a, v48
	v_add_f32_e32 v48, v48, v48
	v_mul_f32_e32 v48, 0x3fb8aa3b, v48
	v_exp_f32_e32 v48, v48
	v_mul_f32_e32 v52, 0.5, v235
	s_waitcnt lgkmcnt(0)
	v_add_f32_e32 v49, v236, v47
	v_add_f32_e32 v48, 1.0, v48
	v_div_scale_f32 v50, s[0:1], v48, v48, 2.0
	v_rcp_f32_e32 v51, v50
	v_div_scale_f32 v53, vcc, 2.0, v48, 2.0
	s_mov_b64 s[0:1], 0
	v_fma_f32 v54, -v50, v51, 1.0
	v_fmac_f32_e32 v51, v54, v51
	v_mul_f32_e32 v54, v53, v51
	v_fma_f32 v55, -v50, v54, v53
	v_fmac_f32_e32 v54, v55, v51
	v_fma_f32 v50, -v50, v54, v53
	v_div_fmas_f32 v50, v50, v51, v54
	v_div_fixup_f32 v48, v50, v48, 2.0
	v_sub_f32_e32 v48, 1.0, v48
	v_add_f32_e32 v48, 1.0, v48
	v_mul_f32_e32 v48, v52, v48
	v_mul_f32_e32 v48, v48, v49
	v_bfe_u32 v49, v48, 16, 1
	v_add3_u32 v50, v48, v49, s56
	v_lshl_add_u64 v[48:49], v[118:119], 0, v[44:45]
	global_store_short_d16_hi v[48:49], v50, off

.LBB0_541:
	v_xor_b32_e32 v44, s25, v75
	v_add_u32_e32 v52, v100, v106
	v_lshlrev_b32_e32 v125, 6, v44
	ds_read_b128 v[44:47], v52 offset:16384
	ds_read_b128 v[52:55], v52 offset:18432
	v_add_lshl_u32 v126, v125, v99, 7
	v_add_u32_e32 v56, 0, v126
	v_add_u32_e32 v48, v56, v106
	ds_read_b128 v[48:51], v48
	v_add_u32_e32 v57, v100, v107
	ds_read_b128 v[58:61], v57 offset:16384
	s_waitcnt lgkmcnt(1)
	v_mfma_f32_16x16x32_bf16 v[44:47], v[44:47], v[48:51], 0
	v_mfma_f32_16x16x32_bf16 v[48:51], v[52:55], v[48:51], 0
	v_add_u32_e32 v52, v56, v107
	ds_read_b128 v[62:65], v52
	ds_read_b128 v[90:93], v57 offset:18432
	s_waitcnt lgkmcnt(0)
	s_barrier
	ds_read_b128 v[54:57], v101
	v_mfma_f32_16x16x32_bf16 v[58:61], v[58:61], v[62:65], v[44:47]
	s_nop 2
	v_add_u32_e32 v45, v104, v126
	v_mfma_f32_16x16x32_bf16 v[46:49], v[90:93], v[62:65], v[48:51]
	s_waitcnt lgkmcnt(0)
	s_nop 1
	v_add_f32_e32 v44, v58, v54
	v_mul_f32_e32 v44, 0xbfb8aa3b, v44
	v_exp_f32_e32 v44, v44
	ds_read_b64 v[92:93], v45
	ds_read_b128 v[50:53], v102
	ds_read_b128 v[62:65], v103
	v_add_f32_e32 v57, v61, v57
	v_add_f32_e32 v44, 1.0, v44
	v_div_scale_f32 v45, s[0:1], v44, v44, 1.0
	v_rcp_f32_e32 v54, v45
	s_waitcnt lgkmcnt(1)
	v_add_f32_e32 v46, v46, v50
	v_mul_f32_e32 v46, 0xbfb8aa3b, v46
	v_add_f32_e32 v47, v47, v51
	v_fma_f32 v58, -v45, v54, 1.0
	v_fmac_f32_e32 v54, v58, v54
	v_div_scale_f32 v58, vcc, 1.0, v44, 1.0
	v_mul_f32_e32 v91, v58, v54
	v_fma_f32 v126, -v45, v91, v58
	v_fmac_f32_e32 v91, v126, v54
	v_fma_f32 v45, -v45, v91, v58
	v_div_fmas_f32 v45, v45, v54, v91
	v_div_fixup_f32 v44, v45, v44, 1.0
	v_mul_f32_e32 v44, 0xc1000000, v44
	s_waitcnt lgkmcnt(0)
	v_mul_f32_e32 v44, v62, v44
	v_mul_f32_e32 v44, 0x3fb8aa3b, v44
	v_exp_f32_e32 v44, v44
	v_mul_f32_e32 v47, 0xbfb8aa3b, v47
	v_mul_f32_e32 v57, 0xbfb8aa3b, v57
	v_exp_f32_e32 v57, v57
	v_fma_f32 v45, -v44, v44, 1.0
	v_max_f32_e32 v45, 0, v45
	v_cmp_gt_f32_e64 s[0:1], s10, v45
	v_mul_f32_e32 v54, 0x4f800000, v45
	v_add_f32_e32 v57, 1.0, v57
	v_cndmask_b32_e64 v58, v45, v54, s[0:1]
	v_sqrt_f32_e32 v45, v58
	v_exp_f32_e32 v54, v46
	v_add_f32_e32 v48, v48, v52
	v_add_f32_e32 v49, v49, v53
	v_add_u32_e32 v46, -1, v45
	v_fma_f32 v50, -v46, v45, v58
	v_cmp_ge_f32_e32 vcc, 0, v50
	v_add_f32_e32 v50, v59, v55
	v_mul_f32_e32 v50, 0xbfb8aa3b, v50
	v_exp_f32_e32 v50, v50
	v_add_u32_e32 v55, 1, v45
	v_cndmask_b32_e32 v46, v45, v46, vcc
	v_fma_f32 v45, -v55, v45, v58
	v_add_f32_e32 v50, 1.0, v50
	v_div_scale_f32 v59, s[26:27], v50, v50, 1.0
	v_rcp_f32_e32 v62, v59
	v_cmp_lt_f32_e32 vcc, 0, v45
	v_mul_f32_e32 v48, 0xbfb8aa3b, v48
	v_mul_f32_e32 v49, 0xbfb8aa3b, v49
	v_fma_f32 v45, -v59, v62, 1.0
	v_cndmask_b32_e32 v46, v46, v55, vcc
	v_fmac_f32_e32 v62, v45, v62
	v_div_scale_f32 v45, vcc, 1.0, v50, 1.0
	v_mul_f32_e32 v126, v45, v62
	v_fma_f32 v127, -v59, v126, v45
	v_fmac_f32_e32 v126, v127, v62
	v_fma_f32 v45, -v59, v126, v45
	v_div_fmas_f32 v45, v45, v62, v126
	v_div_fixup_f32 v45, v45, v50, 1.0
	v_mul_f32_e32 v45, 0xc1000000, v45
	v_mul_f32_e32 v45, v63, v45
	v_mul_f32_e32 v45, 0x3fb8aa3b, v45
	v_exp_f32_e32 v45, v45
	v_mul_f32_e32 v55, 0x37800000, v46
	v_cndmask_b32_e64 v46, v46, v55, s[0:1]
	v_cmp_class_f32_e32 vcc, v58, v169
	v_exp_f32_e32 v48, v48
	v_exp_f32_e32 v49, v49
	v_cndmask_b32_e32 v50, v46, v58, vcc
	v_fma_f32 v46, -v45, v45, 1.0
	v_max_f32_e32 v46, 0, v46
	v_cmp_gt_f32_e64 s[0:1], s10, v46
	v_mul_f32_e32 v55, 0x4f800000, v46
	v_pk_add_f32 v[48:49], v[48:49], 1.0 op_sel_hi:[1,0]
	v_cndmask_b32_e64 v58, v46, v55, s[0:1]
	v_sqrt_f32_e32 v46, v58
	v_exp_f32_e32 v55, v47
	v_lshlrev_b32_e32 v90, 16, v92
	v_and_b32_e32 v91, 0xffff0000, v92
	v_add_u32_e32 v47, -1, v46
	v_fma_f32 v51, -v47, v46, v58
	v_cmp_ge_f32_e32 vcc, 0, v51
	v_add_f32_e32 v51, v60, v56
	v_mul_f32_e32 v51, 0xbfb8aa3b, v51
	v_exp_f32_e32 v51, v51
	v_add_u32_e32 v56, 1, v46
	v_cndmask_b32_e32 v47, v46, v47, vcc
	v_fma_f32 v46, -v56, v46, v58
	v_add_f32_e32 v51, 1.0, v51
	v_div_scale_f32 v59, s[26:27], v51, v51, 1.0
	v_rcp_f32_e32 v60, v59
	v_cmp_lt_f32_e32 vcc, 0, v46
	v_pk_add_f32 v[54:55], v[54:55], 1.0 op_sel_hi:[1,0]
	v_lshlrev_b32_e32 v92, 16, v93
	v_fma_f32 v46, -v59, v60, 1.0
	v_cndmask_b32_e32 v47, v47, v56, vcc
	v_fmac_f32_e32 v60, v46, v60
	v_div_scale_f32 v46, vcc, 1.0, v51, 1.0
	v_mul_f32_e32 v62, v46, v60
	v_fma_f32 v63, -v59, v62, v46
	v_fmac_f32_e32 v62, v63, v60
	v_fma_f32 v46, -v59, v62, v46
	v_div_fmas_f32 v46, v46, v60, v62
	v_div_fixup_f32 v46, v46, v51, 1.0
	v_mul_f32_e32 v46, 0xc1000000, v46
	v_mul_f32_e32 v46, v64, v46
	v_mul_f32_e32 v46, 0x3fb8aa3b, v46
	v_exp_f32_e32 v46, v46
	v_mul_f32_e32 v56, 0x37800000, v47
	v_cndmask_b32_e64 v47, v47, v56, s[0:1]
	v_cmp_class_f32_e32 vcc, v58, v169
	v_div_scale_f32 v59, s[26:27], v57, v57, 1.0
	s_nop 0
	v_cndmask_b32_e32 v51, v47, v58, vcc
	v_fma_f32 v47, -v46, v46, 1.0
	v_max_f32_e32 v47, 0, v47
	v_cmp_gt_f32_e64 s[0:1], s10, v47
	v_mul_f32_e32 v56, 0x4f800000, v47
	v_rcp_f32_e32 v60, v59
	v_cndmask_b32_e64 v56, v47, v56, s[0:1]
	v_sqrt_f32_e32 v47, v56
	v_and_b32_e32 v93, 0xffff0000, v93
	v_add_u32_e32 v52, -1, v47
	v_fma_f32 v58, -v52, v47, v56
	v_cmp_ge_f32_e32 vcc, 0, v58
	v_add_u32_e32 v58, 1, v47
	s_nop 0
	v_cndmask_b32_e32 v52, v47, v52, vcc
	v_fma_f32 v47, -v58, v47, v56
	v_cmp_lt_f32_e32 vcc, 0, v47
	v_fma_f32 v47, -v59, v60, 1.0
	v_fmac_f32_e32 v60, v47, v60
	v_cndmask_b32_e32 v52, v52, v58, vcc
	v_div_scale_f32 v47, vcc, 1.0, v57, 1.0
	v_mul_f32_e32 v61, v47, v60
	v_fma_f32 v62, -v59, v61, v47
	v_fmac_f32_e32 v61, v62, v60
	v_fma_f32 v47, -v59, v61, v47
	v_div_fmas_f32 v47, v47, v60, v61
	v_div_fixup_f32 v47, v47, v57, 1.0
	v_mul_f32_e32 v47, 0xc1000000, v47
	v_mul_f32_e32 v47, v65, v47
	v_mul_f32_e32 v47, 0x3fb8aa3b, v47
	v_exp_f32_e32 v47, v47
	v_mul_f32_e32 v58, 0x37800000, v52
	v_cndmask_b32_e64 v52, v52, v58, s[0:1]
	v_cmp_class_f32_e32 vcc, v56, v169
	s_nop 1
	v_cndmask_b32_e32 v52, v52, v56, vcc
	v_fma_f32 v56, -v47, v47, 1.0
	v_max_f32_e32 v56, 0, v56
	v_cmp_gt_f32_e32 vcc, s10, v56
	v_mul_f32_e32 v57, 0x4f800000, v56
	s_nop 0
	v_cndmask_b32_e32 v56, v56, v57, vcc
	v_sqrt_f32_e32 v57, v56
	s_nop 0
	v_add_u32_e32 v53, -1, v57
	v_fma_f32 v58, -v53, v57, v56
	v_cmp_ge_f32_e64 s[0:1], 0, v58
	v_add_u32_e32 v58, 1, v57
	s_nop 0
	v_cndmask_b32_e64 v53, v57, v53, s[0:1]
	v_fma_f32 v57, -v58, v57, v56
	v_cmp_lt_f32_e64 s[0:1], 0, v57
	s_nop 1
	v_cndmask_b32_e64 v53, v53, v58, s[0:1]
	v_mul_f32_e32 v57, 0x37800000, v53
	v_cndmask_b32_e32 v53, v53, v57, vcc
	v_div_scale_f32 v57, s[0:1], v49, v49, 1.0
	v_rcp_f32_e32 v58, v57
	v_cmp_class_f32_e32 vcc, v56, v169
	s_nop 1
	v_cndmask_b32_e32 v53, v53, v56, vcc
	v_fma_f32 v56, -v57, v58, 1.0
	v_fmac_f32_e32 v58, v56, v58
	v_div_scale_f32 v56, vcc, 1.0, v49, 1.0
	v_mul_f32_e32 v59, v56, v58
	v_fma_f32 v60, -v57, v59, v56
	v_fmac_f32_e32 v59, v60, v58
	v_fma_f32 v56, -v57, v59, v56
	v_div_scale_f32 v57, s[0:1], v48, v48, 1.0
	v_rcp_f32_e32 v60, v57
	v_div_fmas_f32 v56, v56, v58, v59
	v_div_fixup_f32 v49, v56, v49, 1.0
	v_fma_f32 v56, -v57, v60, 1.0
	v_fmac_f32_e32 v60, v56, v60
	v_div_scale_f32 v56, vcc, 1.0, v48, 1.0
	v_mul_f32_e32 v58, v56, v60
	v_fma_f32 v59, -v57, v58, v56
	v_fmac_f32_e32 v58, v59, v60
	v_fma_f32 v56, -v57, v58, v56
	v_div_scale_f32 v57, s[0:1], v55, v55, 1.0
	v_rcp_f32_e32 v59, v57
	v_div_fmas_f32 v56, v56, v60, v58
	v_div_fixup_f32 v48, v56, v48, 1.0
	v_pk_mul_f32 v[48:49], v[48:49], v[52:53]
	v_fma_f32 v56, -v57, v59, 1.0
	v_fmac_f32_e32 v59, v56, v59
	v_div_scale_f32 v56, vcc, 1.0, v55, 1.0
	v_mul_f32_e32 v58, v56, v59
	v_fma_f32 v60, -v57, v58, v56
	v_fmac_f32_e32 v58, v60, v59
	v_fma_f32 v56, -v57, v58, v56
	v_div_scale_f32 v57, s[0:1], v54, v54, 1.0
	v_rcp_f32_e32 v60, v57
	v_div_fmas_f32 v56, v56, v59, v58
	v_div_fixup_f32 v55, v56, v55, 1.0
	v_fma_f32 v56, -v57, v60, 1.0
	v_fmac_f32_e32 v60, v56, v60
	v_div_scale_f32 v56, vcc, 1.0, v54, 1.0
	v_mul_f32_e32 v58, v56, v60
	v_fma_f32 v59, -v57, v58, v56
	v_fmac_f32_e32 v58, v59, v60
	v_fma_f32 v56, -v57, v58, v56
	v_div_fmas_f32 v56, v56, v60, v58
	v_div_fixup_f32 v54, v56, v54, 1.0
	v_pk_mul_f32 v[54:55], v[54:55], v[50:51]
	v_pk_mul_f32 v[50:51], v[48:49], v[92:93]
	v_pk_mul_f32 v[48:49], v[54:55], v[90:91]
	ds_write_b128 v105, v[44:47] offset:32768
	ds_write_b128 v105, v[48:51] offset:50176
	s_waitcnt lgkmcnt(0)
	s_barrier
	s_and_saveexec_b64 s[0:1], s[36:37]
	s_cbranch_execz .LBB0_540
	s_mov_b32 s26, 0
	s_and_b64 s[28:29], s[38:39], exec
	s_cbranch_scc0 .Lscan16_rinit
	v_mov_b32_e32 v44, v74
	ds_read_b32 v46, v44 offset:32768
	ds_read_b32 v47, v44 offset:50176
	ds_read_b32 v50, v44 offset:32848
	ds_read_b32 v51, v44 offset:50256
	ds_read_b32 v54, v44 offset:32928
	ds_read_b32 v55, v44 offset:50336
	ds_read_b32 v58, v44 offset:33008
	ds_read_b32 v59, v44 offset:50416
	ds_read_b32 v62, v44 offset:32768
	ds_read_b32 v63, v44 offset:32768
	ds_read_b32 v90, v44 offset:32768
	ds_read_b32 v91, v44 offset:32768
.Lscan16_fwd:
	s_waitcnt lgkmcnt(10)
	v_fmac_f32_e32 v47, v96, v46
	ds_read_b32 v62, v44 offset:33088
	ds_read_b32 v63, v44 offset:50496
	s_waitcnt lgkmcnt(10)
	v_fmac_f32_e32 v51, v47, v50
	ds_read_b32 v90, v44 offset:33168
	ds_read_b32 v91, v44 offset:50576
	s_waitcnt lgkmcnt(10)
	v_fmac_f32_e32 v55, v51, v54
	ds_read_b32 v126, v44 offset:33248
	ds_read_b32 v127, v44 offset:50656
	s_waitcnt lgkmcnt(10)
	v_fmac_f32_e32 v59, v55, v58
	ds_read_b32 v134, v44 offset:33328
	ds_read_b32 v135, v44 offset:50736
	s_waitcnt lgkmcnt(8)
	ds_write_b32 v44, v47 offset:50176
	ds_write_b32 v44, v51 offset:50256
	ds_write_b32 v44, v55 offset:50336
	ds_write_b32 v44, v59 offset:50416
	v_add_u32_e32 v48, 0x280, v44
	s_waitcnt lgkmcnt(10)
	v_fmac_f32_e32 v63, v59, v62
	ds_read_b32 v46, v48 offset:32768
	ds_read_b32 v47, v48 offset:50176
	s_waitcnt lgkmcnt(10)
	v_fmac_f32_e32 v91, v63, v90
	ds_read_b32 v50, v48 offset:32848
	ds_read_b32 v51, v48 offset:50256
	s_waitcnt lgkmcnt(10)
	v_fmac_f32_e32 v127, v91, v126
	ds_read_b32 v54, v48 offset:32928
	ds_read_b32 v55, v48 offset:50336
	s_waitcnt lgkmcnt(10)
	v_mov_b32_e32 v96, v135
	v_fmac_f32_e32 v96, v127, v134
	ds_read_b32 v58, v48 offset:33008
	ds_read_b32 v59, v48 offset:50416
	s_waitcnt lgkmcnt(8)
	ds_write_b32 v44, v63 offset:50496
	ds_write_b32 v44, v91 offset:50576
	ds_write_b32 v44, v127 offset:50656
	ds_write_b32 v44, v96 offset:50736
	v_mov_b32_e32 v44, v48
	s_add_i32 s26, s26, 8
	s_cmp_lt_u32 s26, 64
	s_cbranch_scc1 .Lscan16_fwd
	s_branch .Lscan16_done
.Lscan16_rinit:
	v_add_u32_e32 v44, 4480, v74
	ds_read_b32 v46, v44 offset:33328
	ds_read_b32 v47, v44 offset:50736
	ds_read_b32 v50, v44 offset:33248
	ds_read_b32 v51, v44 offset:50656
	ds_read_b32 v54, v44 offset:33168
	ds_read_b32 v55, v44 offset:50576
	ds_read_b32 v58, v44 offset:33088
	ds_read_b32 v59, v44 offset:50496
	ds_read_b32 v62, v44 offset:32768
	ds_read_b32 v63, v44 offset:32768
	ds_read_b32 v90, v44 offset:32768
	ds_read_b32 v91, v44 offset:32768
.Lscan16_rev:
	s_waitcnt lgkmcnt(10)
	v_fmac_f32_e32 v47, v96, v46
	ds_read_b32 v62, v44 offset:33008
	ds_read_b32 v63, v44 offset:50416
	s_waitcnt lgkmcnt(10)
	v_fmac_f32_e32 v51, v47, v50
	ds_read_b32 v90, v44 offset:32928
	ds_read_b32 v91, v44 offset:50336
	s_waitcnt lgkmcnt(10)
	v_fmac_f32_e32 v55, v51, v54
	ds_read_b32 v126, v44 offset:32848
	ds_read_b32 v127, v44 offset:50256
	s_waitcnt lgkmcnt(10)
	v_fmac_f32_e32 v59, v55, v58
	ds_read_b32 v134, v44 offset:32768
	ds_read_b32 v135, v44 offset:50176
	s_waitcnt lgkmcnt(8)
	ds_write_b32 v44, v47 offset:50736
	ds_write_b32 v44, v51 offset:50656
	ds_write_b32 v44, v55 offset:50576
	ds_write_b32 v44, v59 offset:50496
	v_add_u32_e32 v48, 0xfffffd80, v44
	s_waitcnt lgkmcnt(10)
	v_fmac_f32_e32 v63, v59, v62
	ds_read_b32 v46, v48 offset:33328
	ds_read_b32 v47, v48 offset:50736
	s_waitcnt lgkmcnt(10)
	v_fmac_f32_e32 v91, v63, v90
	ds_read_b32 v50, v48 offset:33248
	ds_read_b32 v51, v48 offset:50656
	s_waitcnt lgkmcnt(10)
	v_fmac_f32_e32 v127, v91, v126
	ds_read_b32 v54, v48 offset:33168
	ds_read_b32 v55, v48 offset:50576
	s_waitcnt lgkmcnt(10)
	v_mov_b32_e32 v96, v135
	v_fmac_f32_e32 v96, v127, v134
	ds_read_b32 v58, v48 offset:33088
	ds_read_b32 v59, v48 offset:50496
	s_waitcnt lgkmcnt(8)
	ds_write_b32 v44, v63 offset:50416
	ds_write_b32 v44, v91 offset:50336
	ds_write_b32 v44, v127 offset:50256
	ds_write_b32 v44, v96 offset:50176
	v_mov_b32_e32 v44, v48
	s_add_i32 s26, s26, 8
	s_cmp_lt_u32 s26, 64
	s_cbranch_scc1 .Lscan16_rev
.Lscan16_done:
	s_branch .LBB0_540
.LBB0_544:
	s_waitcnt vmcnt(0)
	v_cmp_eq_u32_e32 vcc, 0, v66
	s_barrier
	s_and_saveexec_b64 s[0:1], vcc
	s_cbranch_execz .LBB0_546
	v_lshlrev_b32_e32 v0, 5, v95
	v_lshlrev_b32_e32 v1, 2, v69
	v_lshrrev_b32_e32 v2, 4, v68
	v_or3_b32 v0, v1, v0, v2
	v_readlane_b32 s16, v255, 0
	v_ashrrev_i32_e32 v1, 31, v0
	v_readlane_b32 s17, v255, 1
	buffer_wbl2 sc1
	s_waitcnt vmcnt(0)
	s_waitcnt vmcnt(0)
	s_mov_b64 s[2:3], src_shared_base
	v_lshl_add_u64 v[0:1], v[0:1], 2, s[16:17]
	global_atomic_add v2, v[0:1], v170, off sc0
	s_add_i32 s2, 0, 0x11fe4
	s_waitcnt vmcnt(0)
	buffer_inv sc1
	s_waitcnt vmcnt(0)
	s_cmp_lg_u32 s2, -1
	s_cselect_b32 s2, s2, 0
	s_cselect_b32 s3, s3, 0
	v_mov_b32_e32 v0, s2
	v_mov_b32_e32 v1, s3
	flat_store_dword v[0:1], v2 sc0 sc1
	s_waitcnt vmcnt(0)
